# sample attention: the barrier that frees the bf16 image moved in front of the P.V MFMAs (after this wave's image/P reads), so P.V MFMAs, f32-stage conversion and image writes run without a barrier in
# speedup vs baseline: 1.0126x; 1.0024x over previous
.Lsa_pdone:
	s_or_b64 exec, exec, s[24:25]
	v_add_u32_e32 v40, 0xec00, v221
	s_waitcnt lgkmcnt(0)
	s_barrier
	ds_read2_b32 v[202:203], v40 offset0:52 offset1:84
	ds_read_b64_tr_b16 v[226:227], v43
	ds_read_b64_tr_b16 v[228:229], v44
	ds_read_b64_tr_b16 v[186:187], v43 offset:4096
	ds_read_b64_tr_b16 v[188:189], v44 offset:4096
	ds_read_b64_tr_b16 v[182:183], v43 offset:8192
	ds_read_b64_tr_b16 v[184:185], v44 offset:8192
	ds_read_b64_tr_b16 v[178:179], v43 offset:12288
	ds_read_b64_tr_b16 v[180:181], v44 offset:12288
	s_waitcnt lgkmcnt(8)
	v_pk_mul_f32 v[2:3], v[202:203], v[2:3] op_sel_hi:[0,1]
	v_pk_mul_f32 v[4:5], v[202:203], v[4:5] op_sel_hi:[0,1]
	v_pk_mul_f32 v[6:7], v[202:203], v[6:7] op_sel_hi:[0,1]
	v_pk_mul_f32 v[8:9], v[202:203], v[8:9] op_sel_hi:[0,1]
	v_pk_mul_f32 v[10:11], v[202:203], v[10:11] op_sel_hi:[0,1]
	v_pk_mul_f32 v[12:13], v[202:203], v[12:13] op_sel_hi:[0,1]
	v_pk_mul_f32 v[14:15], v[202:203], v[14:15] op_sel_hi:[0,1]
	v_pk_mul_f32 v[16:17], v[202:203], v[16:17] op_sel_hi:[0,1]
	v_pk_mul_f32 v[18:19], v[202:203], v[18:19] op_sel:[1,0]
	v_pk_mul_f32 v[20:21], v[202:203], v[20:21] op_sel:[1,0]
	v_pk_mul_f32 v[22:23], v[202:203], v[22:23] op_sel:[1,0]
	v_pk_mul_f32 v[24:25], v[202:203], v[24:25] op_sel:[1,0]
	v_pk_mul_f32 v[26:27], v[202:203], v[26:27] op_sel:[1,0]
	v_pk_mul_f32 v[28:29], v[202:203], v[28:29] op_sel:[1,0]
	v_pk_mul_f32 v[30:31], v[202:203], v[30:31] op_sel:[1,0]
	v_pk_mul_f32 v[32:33], v[202:203], v[32:33] op_sel:[1,0]
	s_waitcnt lgkmcnt(4)
	ds_read_b128 v[230:233], v222 offset:37888
	ds_read_b128 v[234:237], v222 offset:42496
	ds_read_b128 v[238:241], v222 offset:37920
	ds_read_b128 v[242:245], v222 offset:42528
	ds_read_b128 v[246:249], v222 offset:37952
	ds_read_b128 v[206:209], v222 offset:42560
	ds_read_b128 v[34:37], v222 offset:37984
	ds_read_b128 v[38:41], v222 offset:42592
	s_waitcnt lgkmcnt(0)
	s_barrier
	v_mfma_f32_32x32x16_bf16 v[2:17], v[226:229], v[230:233], v[2:17]
	v_mfma_f32_32x32x16_bf16 v[18:33], v[226:229], v[234:237], v[18:33]
	v_mfma_f32_32x32x16_bf16 v[2:17], v[186:189], v[238:241], v[2:17]
	v_mfma_f32_32x32x16_bf16 v[18:33], v[186:189], v[242:245], v[18:33]
	v_mfma_f32_32x32x16_bf16 v[2:17], v[182:185], v[246:249], v[2:17]
	v_mfma_f32_32x32x16_bf16 v[18:33], v[182:185], v[206:209], v[18:33]
	v_mfma_f32_32x32x16_bf16 v[2:17], v[178:181], v[34:37], v[2:17]
	v_mfma_f32_32x32x16_bf16 v[18:33], v[178:181], v[38:41], v[18:33]
	s_cmp_lt_u32 s41, s37
	s_cbranch_scc0 .LBB0_828
	s_mov_b64 s[10:11], -1
	s_and_b64 vcc, exec, s[18:19]
	s_cbranch_vccz .LBB0_825
	s_waitcnt lgkmcnt(0)
	s_and_saveexec_b64 s[18:19], s[12:13]
	s_cbranch_execz .LBB0_824
	s_mov_b64 s[20:21], 0
	v_mov_b32_e32 v40, v250
	s_branch .LBB0_818

.LBB0_825:
	s_andn2_b64 vcc, exec, s[10:11]
	s_cbranch_vccnz .LBB0_827
	v_mov_b32_e32 v182, v0
	s_waitcnt vmcnt(0)
	v_lshrrev_b32_e32 v34, 3, v182
	v_bfe_u32 v35, v182, 5, 1
	v_and_or_b32 v34, v34, s28, v35
	v_lshlrev_b32_e32 v35, 5, v182
	v_and_b32_e32 v35, 0x3e0, v35
	v_lshlrev_b32_e32 v34, 10, v34
	v_add3_u32 v42, 0, v35, v34
	v_add_u32_e32 v183, 0xf400, v42
	v_lshlrev_b32_e32 v184, 4, v182
	v_and_b32_e32 v185, 0xffffff80, v184
	v_and_b32_e32 v184, 0x70, v184
	v_add3_u32 v184, s38, v185, v184
	ds_read_b128 v[34:37], v42 offset:62464
	ds_read_b128 v[38:41], v42 offset:62480
	ds_read_b128 v[226:229], v42 offset:64512
	ds_read_b128 v[230:233], v42 offset:64528
	ds_read_b128 v[234:237], v183 offset:4096
	ds_read_b128 v[238:241], v183 offset:4112
	ds_read_b128 v[242:245], v183 offset:6144
	ds_read_b128 v[246:249], v183 offset:6160
	ds_read_b128 v[178:181], v184
	s_waitcnt lgkmcnt(0)
	v_cvt_pk_bf16_f32 v34, v34, v35
	v_cvt_pk_bf16_f32 v35, v36, v37
	v_cvt_pk_bf16_f32 v36, v38, v39
	v_cvt_pk_bf16_f32 v37, v40, v41
	v_cvt_pk_bf16_f32 v226, v226, v227
	v_cvt_pk_bf16_f32 v227, v228, v229
	v_cvt_pk_bf16_f32 v228, v230, v231
	v_cvt_pk_bf16_f32 v229, v232, v233
	v_cvt_pk_bf16_f32 v234, v234, v235
	v_cvt_pk_bf16_f32 v235, v236, v237
	v_cvt_pk_bf16_f32 v236, v238, v239
	v_cvt_pk_bf16_f32 v237, v240, v241
	v_cvt_pk_bf16_f32 v242, v242, v243
	v_cvt_pk_bf16_f32 v243, v244, v245
	v_cvt_pk_bf16_f32 v244, v246, v247
	v_cvt_pk_bf16_f32 v245, v248, v249
	s_waitcnt lgkmcnt(0)
	v_cvt_pk_bf16_f32 v178, v178, v179
	v_cvt_pk_bf16_f32 v179, v180, v181
	v_mov_b32_e32 v180, v0
	s_nop 0
	v_ashrrev_i32_e32 v181, 3, v180
	v_bfe_u32 v183, v180, 5, 1
	v_lshrrev_b32_e32 v188, 2, v181
	v_and_b32_e32 v182, -8, v181
	v_lshlrev_b32_e32 v184, 10, v180
	v_and_b32_e32 v185, 15, v180
	v_and_b32_e32 v188, 2, v188
	v_lshlrev_b32_e32 v189, 2, v183
	v_and_b32_e32 v184, 0x4000, v184
	v_or_b32_e32 v186, v182, v183
	v_bitop3_b32 v202, v189, v185, v188 bitop3:0x36
	v_add_u32_e32 v184, 0, v184
	v_lshlrev_b32_e32 v187, 8, v186
	v_lshlrev_b32_e32 v202, 4, v202
	v_add3_u32 v187, v184, v202, v187
	ds_write_b128 v187, v[34:37]
	v_or_b32_e32 v34, 2, v186
	v_lshlrev_b32_e32 v35, 8, v34
	v_lshlrev_b32_e32 v34, 2, v34
	v_and_b32_e32 v34, 12, v34
	v_bitop3_b32 v34, v34, v185, v188 bitop3:0x36
	v_lshlrev_b32_e32 v34, 4, v34
	v_add3_u32 v34, v184, v34, v35
	ds_write_b128 v34, v[226:229]
	v_or_b32_e32 v34, 4, v182
	v_or_b32_e32 v35, v34, v183
	v_bfe_u32 v34, v34, 2, 2
	v_bitop3_b32 v34, v189, v185, v34 bitop3:0x36
	v_lshlrev_b32_e32 v35, 8, v35
	v_lshlrev_b32_e32 v34, 4, v34
	v_add3_u32 v34, v184, v34, v35
	ds_write_b128 v34, v[234:237]
	v_or_b32_e32 v34, 6, v182
	v_or_b32_e32 v35, v34, v183
	v_lshlrev_b32_e32 v36, 8, v35
	v_lshlrev_b32_e32 v35, 2, v35
	v_and_b32_e32 v35, 12, v35
	v_bfe_u32 v34, v34, 2, 2
	v_bitop3_b32 v34, v35, v185, v34 bitop3:0x36
	v_lshlrev_b32_e32 v34, 4, v34
	v_add3_u32 v34, v184, v34, v36
	ds_write_b128 v34, v[242:245]
	v_lshlrev_b32_e32 v34, 2, v180
	v_and_b32_e32 v34, 28, v34
	v_mad_u64_u32 v[34:35], s[10:11], v181, 40, v[34:35]
	v_lshl_add_u32 v34, v34, 1, 0
	ds_write_b64 v34, v[178:179] offset:32768
